# scan: second wave of every SIMD starts each 32-step chunk 64 cycles late (stagger)
# speedup vs baseline: 1.0084x; 1.0026x over previous
; #define LAS __attribute__((address_space(3)))
; __device__ __forceinline__ void phase_scan(CParams& P, LAS unsigned char* lds) {
;     ...
;             for (int c = 0; c < NCH; ++c) {
;                 __syncthreads();
;                 const LAS float* base = lf + (c & 1) * BUFF + 8 * oct;
;                 SC_LOAD(A, base);
.Lsc_noC5:
.Lsc_noload:
	s_cmp_lt_u32 s28, 4
	s_cbranch_scc1 .Lsc_nostag
	s_sleep 1
